# R3 first state stage: the 64 fragment reads run seven fragments ahead of the MFMAs through registers that are dead in that stage
# speedup vs baseline: 1.0006x; 1.0006x over previous
.LBB0_1086:
	v_mul_f32_e32 v34, 0xbfb8aa3b, v33
	v_rndne_f32_e32 v35, v34
	v_sub_f32_e32 v36, v34, v35
	v_fma_f32 v34, v33, s85, -v34
	v_fmac_f32_e32 v34, 0xb2a5705f, v33
	v_add_f32_e32 v34, v36, v34
	v_exp_f32_e32 v34, v34
	v_cvt_i32_f32_e32 v35, v35
	v_cmp_nlt_f32_e32 vcc, s86, v33
	s_add_u32 s58, s42, 0x10000
	s_addc_u32 s59, s96, 0
	v_ldexp_f32 v34, v34, v35
	v_cndmask_b32_e32 v34, 0, v34, vcc
	v_cmp_ngt_f32_e32 vcc, s87, v33
	s_add_u32 s60, s97, 0x10000
	s_addc_u32 s61, s18, 0
	v_cndmask_b32_e32 v79, v224, v34, vcc
	v_add_f32_e32 v159, 1.0, v79
	v_frexp_mant_f32_e32 v33, v159
	v_cmp_gt_f32_e64 s[16:17], s89, v33
	v_mul_f32_e32 v33, 0xbfb8aa3b, v32
	v_rndne_f32_e32 v34, v33
	v_sub_f32_e32 v35, v33, v34
	v_fma_f32 v33, v32, s85, -v33
	v_fmac_f32_e32 v33, 0xb2a5705f, v32
	v_add_f32_e32 v33, v35, v33
	v_exp_f32_e32 v33, v33
	v_cvt_i32_f32_e32 v34, v34
	v_cmp_nlt_f32_e32 vcc, s86, v32
	s_mov_b32 m0, s21
	v_cmp_neq_f32_e64 s[10:11], s88, v79
	v_ldexp_f32 v33, v33, v34
	v_cndmask_b32_e32 v33, 0, v33, vcc
	v_cmp_ngt_f32_e32 vcc, s87, v32
	v_cmp_lt_f32_e64 s[12:13], |v79|, s91
	s_nop 0
	v_cndmask_b32_e32 v78, v224, v33, vcc
	v_add_f32_e32 v162, 1.0, v78
	v_frexp_mant_f32_e32 v32, v162
	v_cmp_gt_f32_e64 s[14:15], s89, v32
	ds_read_b128 v[80:83], v213
	ds_read_b128 v[84:87], v213 offset:34816
	ds_read_b128 v[88:91], v213 offset:64
	ds_read_b128 v[92:95], v213 offset:34880
	ds_read_b128 v[96:99], v213 offset:128
	ds_read_b128 v[100:103], v213 offset:34944
	ds_read_b128 v[104:107], v213 offset:192
	s_waitcnt lgkmcnt(6)
	v_mfma_f32_16x16x32_bf16 v[32:35], v[80:83], v[0:3], 0
	ds_read_b128 v[108:111], v213 offset:35008
	v_cmp_neq_f32_e64 s[6:7], s88, v78
	s_waitcnt lgkmcnt(6)
	v_mfma_f32_16x16x32_bf16 v[36:39], v[84:87], v[0:3], 0
	ds_read_b128 v[80:83], v213 offset:256
	v_cmp_lt_f32_e64 s[8:9], |v78|, s91
	s_waitcnt lgkmcnt(6)
	v_mfma_f32_16x16x32_bf16 v[32:35], v[88:91], v[4:7], v[32:35]
	ds_read_b128 v[84:87], v213 offset:35072
	s_and_b64 vcc, exec, s[4:5]
	s_waitcnt lgkmcnt(6)
	v_mfma_f32_16x16x32_bf16 v[36:39], v[92:95], v[4:7], v[36:39]
	ds_read_b128 v[88:91], v213 offset:320
	s_waitcnt lgkmcnt(6)
	v_mfma_f32_16x16x32_bf16 v[32:35], v[96:99], v[8:11], v[32:35]
	ds_read_b128 v[92:95], v213 offset:35136
	s_waitcnt lgkmcnt(6)
	v_mfma_f32_16x16x32_bf16 v[36:39], v[100:103], v[8:11], v[36:39]
	ds_read_b128 v[96:99], v213 offset:384
	s_waitcnt lgkmcnt(6)
	v_mfma_f32_16x16x32_bf16 v[32:35], v[104:107], v[12:15], v[32:35]
	ds_read_b128 v[100:103], v213 offset:35200
	s_waitcnt lgkmcnt(6)
	v_mfma_f32_16x16x32_bf16 v[36:39], v[108:111], v[12:15], v[36:39]
	ds_read_b128 v[104:107], v213 offset:448
	s_waitcnt lgkmcnt(6)
	v_mfma_f32_16x16x32_bf16 v[32:35], v[80:83], v[16:19], v[32:35]
	ds_read_b128 v[108:111], v213 offset:35264
	s_waitcnt lgkmcnt(6)
	v_mfma_f32_16x16x32_bf16 v[36:39], v[84:87], v[16:19], v[36:39]
	ds_read_b128 v[80:83], v213 offset:8704
	s_waitcnt lgkmcnt(6)
	v_mfma_f32_16x16x32_bf16 v[32:35], v[88:91], v[20:23], v[32:35]
	ds_read_b128 v[84:87], v213 offset:43520
	s_waitcnt lgkmcnt(6)
	v_mfma_f32_16x16x32_bf16 v[36:39], v[92:95], v[20:23], v[36:39]
	ds_read_b128 v[88:91], v213 offset:8768
	s_waitcnt lgkmcnt(6)
	v_mfma_f32_16x16x32_bf16 v[32:35], v[96:99], v[24:27], v[32:35]
	ds_read_b128 v[92:95], v213 offset:43584
	s_waitcnt lgkmcnt(6)
	v_mfma_f32_16x16x32_bf16 v[36:39], v[100:103], v[24:27], v[36:39]
	ds_read_b128 v[96:99], v213 offset:8832
	s_waitcnt lgkmcnt(6)
	v_mfma_f32_16x16x32_bf16 v[32:35], v[104:107], v[28:31], v[32:35]
	ds_read_b128 v[100:103], v213 offset:43648
	s_waitcnt lgkmcnt(6)
	v_mfma_f32_16x16x32_bf16 v[36:39], v[108:111], v[28:31], v[36:39]
	ds_read_b128 v[104:107], v213 offset:8896
	s_waitcnt lgkmcnt(6)
	v_mfma_f32_16x16x32_bf16 v[40:43], v[80:83], v[0:3], 0
	ds_read_b128 v[108:111], v213 offset:43712
	s_waitcnt lgkmcnt(6)
	v_mfma_f32_16x16x32_bf16 v[44:47], v[84:87], v[0:3], 0
	ds_read_b128 v[80:83], v213 offset:8960
	s_waitcnt lgkmcnt(6)
	v_mfma_f32_16x16x32_bf16 v[40:43], v[88:91], v[4:7], v[40:43]
	ds_read_b128 v[84:87], v213 offset:43776
	s_waitcnt lgkmcnt(6)
	v_mfma_f32_16x16x32_bf16 v[44:47], v[92:95], v[4:7], v[44:47]
	ds_read_b128 v[88:91], v213 offset:9024
	s_waitcnt lgkmcnt(6)
	v_mfma_f32_16x16x32_bf16 v[40:43], v[96:99], v[8:11], v[40:43]
	ds_read_b128 v[92:95], v213 offset:43840
	s_waitcnt lgkmcnt(6)
	v_mfma_f32_16x16x32_bf16 v[44:47], v[100:103], v[8:11], v[44:47]
	ds_read_b128 v[96:99], v213 offset:9088
	s_waitcnt lgkmcnt(6)
	v_mfma_f32_16x16x32_bf16 v[40:43], v[104:107], v[12:15], v[40:43]
	ds_read_b128 v[100:103], v213 offset:43904
	s_waitcnt lgkmcnt(6)
	v_mfma_f32_16x16x32_bf16 v[44:47], v[108:111], v[12:15], v[44:47]
	ds_read_b128 v[104:107], v213 offset:9152
	s_waitcnt lgkmcnt(6)
	v_mfma_f32_16x16x32_bf16 v[40:43], v[80:83], v[16:19], v[40:43]
	ds_read_b128 v[108:111], v213 offset:43968
	s_waitcnt lgkmcnt(6)
	v_mfma_f32_16x16x32_bf16 v[44:47], v[84:87], v[16:19], v[44:47]
	ds_read_b128 v[80:83], v213 offset:17408
	s_waitcnt lgkmcnt(6)
	v_mfma_f32_16x16x32_bf16 v[40:43], v[88:91], v[20:23], v[40:43]
	ds_read_b128 v[84:87], v213 offset:52224
	s_waitcnt lgkmcnt(6)
	v_mfma_f32_16x16x32_bf16 v[44:47], v[92:95], v[20:23], v[44:47]
	ds_read_b128 v[88:91], v213 offset:17472
	s_waitcnt lgkmcnt(6)
	v_mfma_f32_16x16x32_bf16 v[40:43], v[96:99], v[24:27], v[40:43]
	ds_read_b128 v[92:95], v213 offset:52288
	s_waitcnt lgkmcnt(6)
	v_mfma_f32_16x16x32_bf16 v[44:47], v[100:103], v[24:27], v[44:47]
	ds_read_b128 v[96:99], v213 offset:17536
	s_waitcnt lgkmcnt(6)
	v_mfma_f32_16x16x32_bf16 v[40:43], v[104:107], v[28:31], v[40:43]
	ds_read_b128 v[100:103], v213 offset:52352
	s_waitcnt lgkmcnt(6)
	v_mfma_f32_16x16x32_bf16 v[44:47], v[108:111], v[28:31], v[44:47]
	ds_read_b128 v[104:107], v213 offset:17600
	s_waitcnt lgkmcnt(6)
	v_mfma_f32_16x16x32_bf16 v[48:51], v[80:83], v[0:3], 0
	ds_read_b128 v[108:111], v213 offset:52416
	s_waitcnt lgkmcnt(6)
	v_mfma_f32_16x16x32_bf16 v[52:55], v[84:87], v[0:3], 0
	ds_read_b128 v[80:83], v213 offset:17664
	s_waitcnt lgkmcnt(6)
	v_mfma_f32_16x16x32_bf16 v[48:51], v[88:91], v[4:7], v[48:51]
	ds_read_b128 v[84:87], v213 offset:52480
	s_waitcnt lgkmcnt(6)
	v_mfma_f32_16x16x32_bf16 v[52:55], v[92:95], v[4:7], v[52:55]
	ds_read_b128 v[88:91], v213 offset:17728
	s_waitcnt lgkmcnt(6)
	v_mfma_f32_16x16x32_bf16 v[48:51], v[96:99], v[8:11], v[48:51]
	ds_read_b128 v[92:95], v213 offset:52544
	s_waitcnt lgkmcnt(6)
	v_mfma_f32_16x16x32_bf16 v[52:55], v[100:103], v[8:11], v[52:55]
	ds_read_b128 v[96:99], v213 offset:17792
	s_waitcnt lgkmcnt(6)
	v_mfma_f32_16x16x32_bf16 v[48:51], v[104:107], v[12:15], v[48:51]
	ds_read_b128 v[100:103], v213 offset:52608
	s_waitcnt lgkmcnt(6)
	v_mfma_f32_16x16x32_bf16 v[52:55], v[108:111], v[12:15], v[52:55]
	ds_read_b128 v[104:107], v213 offset:17856
	s_waitcnt lgkmcnt(6)
	v_mfma_f32_16x16x32_bf16 v[48:51], v[80:83], v[16:19], v[48:51]
	ds_read_b128 v[108:111], v213 offset:52672
	s_waitcnt lgkmcnt(6)
	v_mfma_f32_16x16x32_bf16 v[52:55], v[84:87], v[16:19], v[52:55]
	ds_read_b128 v[80:83], v213 offset:26112
	s_waitcnt lgkmcnt(6)
	v_mfma_f32_16x16x32_bf16 v[48:51], v[88:91], v[20:23], v[48:51]
	ds_read_b128 v[84:87], v213 offset:60928
	s_waitcnt lgkmcnt(6)
	v_mfma_f32_16x16x32_bf16 v[52:55], v[92:95], v[20:23], v[52:55]
	ds_read_b128 v[88:91], v213 offset:26176
	s_waitcnt lgkmcnt(6)
	v_mfma_f32_16x16x32_bf16 v[48:51], v[96:99], v[24:27], v[48:51]
	ds_read_b128 v[92:95], v213 offset:60992
	s_waitcnt lgkmcnt(6)
	v_mfma_f32_16x16x32_bf16 v[52:55], v[100:103], v[24:27], v[52:55]
	ds_read_b128 v[96:99], v213 offset:26240
	s_waitcnt lgkmcnt(6)
	v_mfma_f32_16x16x32_bf16 v[48:51], v[104:107], v[28:31], v[48:51]
	ds_read_b128 v[100:103], v213 offset:61056
	s_waitcnt lgkmcnt(6)
	v_mfma_f32_16x16x32_bf16 v[52:55], v[108:111], v[28:31], v[52:55]
	ds_read_b128 v[104:107], v213 offset:26304
	s_waitcnt lgkmcnt(6)
	v_mfma_f32_16x16x32_bf16 v[56:59], v[80:83], v[0:3], 0
	ds_read_b128 v[108:111], v213 offset:61120
	s_waitcnt lgkmcnt(6)
	v_mfma_f32_16x16x32_bf16 v[60:63], v[84:87], v[0:3], 0
	ds_read_b128 v[80:83], v213 offset:26368
	s_waitcnt lgkmcnt(6)
	v_mfma_f32_16x16x32_bf16 v[56:59], v[88:91], v[4:7], v[56:59]
	ds_read_b128 v[84:87], v213 offset:61184
	s_waitcnt lgkmcnt(6)
	v_mfma_f32_16x16x32_bf16 v[60:63], v[92:95], v[4:7], v[60:63]
	ds_read_b128 v[88:91], v213 offset:26432
	s_waitcnt lgkmcnt(6)
	v_mfma_f32_16x16x32_bf16 v[56:59], v[96:99], v[8:11], v[56:59]
	ds_read_b128 v[92:95], v213 offset:61248
	s_waitcnt lgkmcnt(6)
	v_mfma_f32_16x16x32_bf16 v[60:63], v[100:103], v[8:11], v[60:63]
	ds_read_b128 v[96:99], v213 offset:26496
	s_waitcnt lgkmcnt(6)
	v_mfma_f32_16x16x32_bf16 v[56:59], v[104:107], v[12:15], v[56:59]
	ds_read_b128 v[100:103], v213 offset:61312
	s_waitcnt lgkmcnt(6)
	v_mfma_f32_16x16x32_bf16 v[60:63], v[108:111], v[12:15], v[60:63]
	ds_read_b128 v[64:67], v213 offset:26560
	s_waitcnt lgkmcnt(6)
	v_mfma_f32_16x16x32_bf16 v[56:59], v[80:83], v[16:19], v[56:59]
	ds_read_b128 v[68:71], v213 offset:61376
	s_waitcnt lgkmcnt(6)
	v_mfma_f32_16x16x32_bf16 v[60:63], v[84:87], v[16:19], v[60:63]
	s_waitcnt lgkmcnt(5)
	v_mfma_f32_16x16x32_bf16 v[56:59], v[88:91], v[20:23], v[56:59]
	s_waitcnt lgkmcnt(4)
	v_mfma_f32_16x16x32_bf16 v[60:63], v[92:95], v[20:23], v[60:63]
	s_waitcnt lgkmcnt(3)
	v_mfma_f32_16x16x32_bf16 v[56:59], v[96:99], v[24:27], v[56:59]
	s_waitcnt lgkmcnt(2)
	v_mfma_f32_16x16x32_bf16 v[60:63], v[100:103], v[24:27], v[60:63]
	s_waitcnt vmcnt(0)
	s_waitcnt lgkmcnt(1)
	v_mfma_f32_16x16x32_bf16 v[56:59], v[64:67], v[28:31], v[56:59]
	v_lshl_add_u64 v[64:65], s[58:59], 0, v[132:133]
	s_waitcnt lgkmcnt(0)
	s_barrier
	global_load_lds_dwordx4 v[64:65], off
	v_lshl_add_u64 v[64:65], s[60:61], 0, v[132:133]
	s_mov_b32 m0, s48
	v_mfma_f32_16x16x32_bf16 v[60:63], v[68:71], v[28:31], v[60:63]
	global_load_lds_dwordx4 v[64:65], off
	v_lshl_add_u64 v[64:65], s[58:59], 0, v[134:135]
	s_mov_b32 m0, s49
	s_nop 0
	global_load_lds_dwordx4 v[64:65], off
	v_lshl_add_u64 v[64:65], s[60:61], 0, v[134:135]
	s_mov_b32 m0, s62
	s_nop 0
	global_load_lds_dwordx4 v[64:65], off
	v_lshl_add_u64 v[64:65], s[58:59], 0, v[136:137]
	s_mov_b32 m0, s63
	s_nop 0
	global_load_lds_dwordx4 v[64:65], off
	v_lshl_add_u64 v[64:65], s[60:61], 0, v[136:137]
	s_mov_b32 m0, s64
	s_nop 0
	global_load_lds_dwordx4 v[64:65], off
	v_lshl_add_u64 v[64:65], s[58:59], 0, v[138:139]
	s_mov_b32 m0, s65
	s_nop 0
	global_load_lds_dwordx4 v[64:65], off
	v_lshl_add_u64 v[64:65], s[60:61], 0, v[138:139]
	s_mov_b32 m0, s66
	s_nop 0
	global_load_lds_dwordx4 v[64:65], off
	s_cbranch_vccnz .LBB0_1088
	s_mov_b32 m0, s82
	v_lshl_add_u64 v[66:67], s[58:59], 0, v[140:141]
	v_lshl_add_u64 v[64:65], s[60:61], 0, v[140:141]
	global_load_lds_dwordx4 v[66:67], off
	s_add_i32 m0, s82, 0x8800
	s_nop 0
	global_load_lds_dwordx4 v[64:65], off
